# phase 1->2 grid barrier: arrive after adaLN before the w_gate/w_up transposes, deferred wait; plus final barrier replaced by counter handoff
# speedup vs baseline: 1.0081x; 1.0081x over previous
.LBB0_81:
	s_cmp_lt_i32 s93, 3
	s_cbranch_scc1 .Lb1_noarr
	s_waitcnt vmcnt(0)
	s_barrier
	v_writelane_b32 v243, s10, 0
	v_writelane_b32 v243, s19, 1
	v_writelane_b32 v243, s21, 2
	v_writelane_b32 v243, s72, 3
	v_writelane_b32 v243, s73, 4
	v_writelane_b32 v243, s74, 5
	v_writelane_b32 v243, s75, 6
	v_writelane_b32 v243, s76, 7
	v_writelane_b32 v243, s77, 8
	s_and_saveexec_b64 s[4:5], s[94:95]
	s_cbranch_execz .Lb1_arrdone
	v_mov_b32_e32 v140, 0x24160
	ds_read_b32 v143, v140
	ds_read_b32 v140, v140 offset:4
	s_waitcnt lgkmcnt(0)
.Lb1_115:
	s_mov_b64 s[20:21], exec
	s_lshl_b32 s6, s96, 8
	v_mbcnt_lo_u32_b32 v142, s20, 0
	s_add_u32 s10, s84, s6
	v_mbcnt_hi_u32_b32 v142, s21, v142
	s_addc_u32 s11, s85, 0
	v_cmp_eq_u32_e32 vcc, 0, v142
	s_and_saveexec_b64 s[22:23], vcc
	s_cbranch_execz .Lb1_117
	s_bcnt1_i32_b64 s6, s[20:21]
	v_mov_b32_e32 v144, 0x1000
	v_mov_b32_e32 v145, s6
	global_atomic_add v144, v144, v145, s[10:11] offset:1024 sc0
.Lb1_117:
	s_or_b64 exec, exec, s[22:23]
	v_cvt_f32_u32_e32 v145, v143
	s_waitcnt vmcnt(0)
	v_readfirstlane_b32 s6, v144
	v_sub_u32_e32 v144, 0, v143
	v_rcp_iflag_f32_e32 v145, v145
	v_add_u32_e32 v146, s6, v142
	v_mul_f32_e32 v145, 0x4f7ffffe, v145
	v_cvt_u32_f32_e32 v145, v145
	v_mul_lo_u32 v142, v144, v145
	v_mul_hi_u32 v142, v145, v142
	v_add_u32_e32 v142, v145, v142
	v_mul_hi_u32 v142, v146, v142
	v_mul_lo_u32 v144, v142, v143
	v_sub_u32_e32 v144, v146, v144
	v_add_u32_e32 v145, 1, v142
	v_cmp_ge_u32_e32 vcc, v144, v143
	s_nop 1
	v_cndmask_b32_e32 v142, v142, v145, vcc
	v_sub_u32_e32 v145, v144, v143
	v_cndmask_b32_e32 v144, v144, v145, vcc
	v_add_u32_e32 v145, 1, v142
	v_cmp_ge_u32_e32 vcc, v144, v143
	v_add_u32_e32 v144, 1, v146
	s_nop 0
	v_cndmask_b32_e32 v142, v142, v145, vcc
	v_mul_lo_u32 v145, v143, v142
	v_add_u32_e32 v143, v145, v143
	v_cmp_ne_u32_e32 vcc, v144, v143
	s_and_saveexec_b64 s[6:7], vcc
	s_xor_b64 s[20:21], exec, s[6:7]
	s_cbranch_execz .Lb1_131
	s_waitcnt lgkmcnt(0)
	s_branch .Lb1_defer
	v_mov_b32_e32 v140, 0x2000
	global_load_dword v140, v140, s[10:11] offset:1024 sc1
	s_add_u32 s56, s10, 0x2400
	s_addc_u32 s57, s11, 0
	s_waitcnt vmcnt(0)
	v_cmp_eq_u32_e32 vcc, v140, v142
	s_and_saveexec_b64 s[22:23], vcc
	s_cbranch_execz .Lb1_130
	s_add_u32 s54, s68, 0x4200
	s_addc_u32 s55, s69, 0
	s_mov_b32 s6, 1
	s_mov_b64 s[58:59], 0
	v_mov_b32_e32 v140, 0
	s_branch .Lb1_121

.Lb1_123:
	global_load_dword v143, v140, s[56:57] sc1
	s_add_i32 s6, s6, 1
	s_mov_b64 s[76:77], -1
	s_waitcnt vmcnt(0)
	v_cmp_ne_u32_e32 vcc, v143, v142
	s_orn2_b64 s[74:75], vcc, exec
	s_branch .Lb1_120
.Lb1_124:
	global_load_dword v143, v140, s[54:55] sc1
	s_waitcnt vmcnt(0)
	v_cmp_eq_u32_e32 vcc, 0, v143
	s_cbranch_vccnz .Lb1_126
	s_mov_b64 s[76:77], -1
	s_branch .Lb1_120

.Lb1_127:
	s_or_b64 exec, exec, s[58:59]
	s_xor_b64 s[6:7], s[72:73], -1
	s_and_saveexec_b64 s[16:17], s[6:7]
	s_xor_b64 s[16:17], exec, s[16:17]
	s_cbranch_execz .Lb1_130
	s_mov_b64 s[56:57], exec
	v_mbcnt_lo_u32_b32 v140, s56, 0
	v_mbcnt_hi_u32_b32 v140, s57, v140
	v_cmp_eq_u32_e32 vcc, 0, v140
	s_and_b64 s[6:7], exec, vcc
	s_mov_b64 exec, s[6:7]
	s_cbranch_execz .Lb1_130
	s_bcnt1_i32_b64 s6, s[56:57]
	v_mov_b32_e32 v140, 0
	v_mov_b32_e32 v142, s6
	global_atomic_add v140, v142, s[54:55]

.Lb1_131:
	s_andn2_saveexec_b64 s[6:7], s[20:21]
	s_cbranch_execz .Lb1_arrdone
	s_mov_b64 s[20:21], exec
	buffer_wbl2 sc1
	s_waitcnt lgkmcnt(0)
	s_waitcnt vmcnt(0)
	v_mbcnt_lo_u32_b32 v142, s20, 0
	v_mbcnt_hi_u32_b32 v142, s21, v142
	v_cmp_eq_u32_e32 vcc, 0, v142
	s_and_saveexec_b64 s[22:23], vcc
	s_cbranch_execz .Lb1_134
	s_bcnt1_i32_b64 s6, s[20:21]
	v_mov_b32_e32 v143, 0x7000
	v_mov_b32_e32 v144, s6
	global_atomic_add v143, v143, v144, s[68:69] offset:1024 sc0
.Lb1_134:
	s_or_b64 exec, exec, s[22:23]
	v_cvt_f32_u32_e32 v144, v140
	s_waitcnt vmcnt(0)
	v_readfirstlane_b32 s6, v143
	s_add_u32 s22, s68, 0x7500
	s_addc_u32 s23, s69, 0
	v_rcp_iflag_f32_e32 v144, v144
	v_add_u32_e32 v142, s6, v142
	v_add_u32_e32 v145, 1, v142
	s_mov_b64 s[54:55], -1
	v_mul_f32_e32 v143, 0x4f7ffffe, v144
	v_cvt_u32_f32_e32 v143, v143
	v_sub_u32_e32 v144, 0, v140
	v_mul_lo_u32 v144, v144, v143
	v_mul_hi_u32 v144, v143, v144
	v_add_u32_e32 v143, v143, v144
	v_mul_hi_u32 v143, v142, v143
	v_mul_lo_u32 v144, v143, v140
	v_sub_u32_e32 v142, v142, v144
	v_add_u32_e32 v146, 1, v143
	v_cmp_ge_u32_e32 vcc, v142, v140
	v_sub_u32_e32 v144, v142, v140
	s_nop 0
	v_cndmask_b32_e32 v143, v143, v146, vcc
	v_cndmask_b32_e32 v142, v142, v144, vcc
	v_add_u32_e32 v144, 1, v143
	v_cmp_ge_u32_e32 vcc, v142, v140
	s_nop 1
	v_cndmask_b32_e32 v144, v143, v144, vcc
	v_mul_lo_u32 v142, v140, v144
	v_add_u32_e32 v140, v142, v140
	v_cmp_ne_u32_e32 vcc, v145, v140
	v_mov_b64_e32 v[142:143], s[22:23]
	s_and_saveexec_b64 s[20:21], vcc
	s_cbranch_execz .Lb1_146
	v_mov_b32_e32 v140, 0
	global_load_dword v142, v140, s[22:23] sc1
	s_mov_b64 s[58:59], 0
	s_waitcnt vmcnt(0)
	v_cmp_eq_u32_e32 vcc, v142, v144
	s_and_saveexec_b64 s[56:57], vcc
	s_cbranch_execz .Lb1_145
	s_add_u32 s54, s68, 0x4200
	s_addc_u32 s55, s69, 0
	s_mov_b32 s6, 1
	s_branch .Lb1_138

.Lb1_140:
	global_load_dword v142, v140, s[22:23] sc1
	s_add_i32 s6, s6, 1
	s_mov_b64 s[74:75], -1
	s_waitcnt vmcnt(0)
	v_cmp_ne_u32_e32 vcc, v142, v144
	s_orn2_b64 s[78:79], vcc, exec
	s_branch .Lb1_137
.Lb1_141:
	global_load_dword v142, v140, s[54:55] sc1
	s_waitcnt vmcnt(0)
	v_cmp_eq_u32_e32 vcc, 0, v142
	s_cbranch_vccnz .Lb1_143
	s_mov_b64 s[74:75], -1
	s_mov_b64 s[78:79], -1
	s_branch .Lb1_137

.Lb1_145:
	s_or_b64 exec, exec, s[56:57]
	v_mov_b64_e32 v[142:143], s[54:55]
	s_orn2_b64 s[54:55], s[58:59], exec
.Lb1_146:
	s_or_b64 exec, exec, s[20:21]
	s_and_saveexec_b64 s[20:21], s[54:55]
	s_cbranch_execz .Lb1_148
	v_mov_b32_e32 v140, 1
	global_atomic_add v[142:143], v140, off
.Lb1_148:
	s_or_b64 exec, exec, s[20:21]
	s_mov_b64 s[20:21], exec
	v_mbcnt_lo_u32_b32 v140, s20, 0
	v_mbcnt_hi_u32_b32 v140, s21, v140
	v_cmp_eq_u32_e32 vcc, 0, v140
	s_waitcnt vmcnt(0)
	buffer_inv sc1
	s_and_saveexec_b64 s[22:23], vcc
	s_cbranch_execz .Lb1_150
	s_bcnt1_i32_b64 s6, s[20:21]
	v_mov_b32_e32 v140, 0x2000
	v_mov_b32_e32 v142, s6
	global_atomic_add v140, v142, s[10:11] offset:1024

.Lb1_arrdone:
	s_or_b64 exec, exec, s[4:5]
	s_waitcnt lgkmcnt(0)
	v_readlane_b32 s10, v243, 0
	v_readlane_b32 s19, v243, 1
	v_readlane_b32 s21, v243, 2
	v_readlane_b32 s72, v243, 3
	v_readlane_b32 s73, v243, 4
	v_readlane_b32 s74, v243, 5
	v_readlane_b32 s75, v243, 6
	v_readlane_b32 s76, v243, 7
	v_readlane_b32 s77, v243, 8
	s_branch .Lb1_noarr
.Lb1_defer:
	s_add_u32 s56, s10, 0x2400
	s_addc_u32 s57, s11, 0
	v_mov_b32_e32 v140, 0x24200
	v_mov_b32_e32 v144, 1
	v_mov_b32_e32 v145, s56
	v_mov_b32_e32 v146, s57
	ds_write_b32 v140, v144
	ds_write_b32 v140, v142 offset:4
	ds_write_b32 v140, v145 offset:8
	ds_write_b32 v140, v146 offset:12
	s_branch .Lb1_131

.LBB0_98:
.LBB0_99:
	s_barrier
	s_and_saveexec_b64 s[4:5], s[94:95]
	s_cbranch_execz .LBB0_151
	v_mov_b32_e32 v1, 0x24200
	s_waitcnt vmcnt(0) expcnt(0) lgkmcnt(0)
	ds_read_b32 v26, v1
	s_waitcnt lgkmcnt(0)
	v_readfirstlane_b32 s6, v26
	s_cmp_eq_u32 s6, 0
	s_cbranch_scc1 .LBB0_151
	ds_read_b32 v26, v1 offset:8
	s_waitcnt lgkmcnt(0)
	v_readfirstlane_b32 s10, v26
	ds_read_b32 v26, v1 offset:12
	s_waitcnt lgkmcnt(0)
	v_readfirstlane_b32 s11, v26
	ds_read_b32 v26, v1 offset:4
	s_waitcnt lgkmcnt(0)
	v_mov_b32_e32 v27, 0
	ds_write_b32 v1, v27
	s_mov_b32 s6, 0
	s_nop 4
.Lb1_spin:
	global_load_dword v1, v27, s[10:11] sc1
	s_waitcnt vmcnt(0)
	v_cmp_ne_u32_e32 vcc, v1, v26
	s_cbranch_vccnz .Lb1_rel
	s_sleep 1
	s_add_i32 s6, s6, 1
	s_cmp_lt_u32 s6, 0x100000
	s_cbranch_scc1 .Lb1_spin
.Lb1_rel:
	buffer_inv sc1
	s_waitcnt vmcnt(0)
.LBB0_151:
	s_or_b64 exec, exec, s[4:5]
	s_mov_b64 s[4:5], -1
	s_and_b64 vcc, exec, s[2:3]
	s_waitcnt lgkmcnt(0)
	s_barrier
	s_cbranch_vccz .LBB0_157
	v_lshl_add_u32 v1, v0, 2, 0
	s_movk_i32 s2, 0x280
	v_add_u32_e32 v26, 0xffffff00, v1
	v_cmp_gt_u32_e32 vcc, s2, v0
	s_waitcnt vmcnt(1)
	ds_write_b32 v26, v14
	ds_write2st64_b32 v1, v15, v16 offset0:15 offset1:31
	s_waitcnt vmcnt(0)
	ds_write2st64_b32 v1, v17, v6 offset0:47 offset1:63
	ds_write2st64_b32 v1, v7, v8 offset0:79 offset1:95
	ds_write_b32 v1, v9 offset:28416
	s_and_saveexec_b64 s[2:3], vcc
	s_cbranch_execz .LBB0_154
	ds_write2st64_b32 v1, v2, v3 offset0:6 offset1:22
	ds_write2st64_b32 v1, v4, v5 offset0:38 offset1:54
	ds_write2st64_b32 v1, v10, v11 offset0:70 offset1:86
	ds_write2st64_b32 v1, v12, v13 offset0:102 offset1:118

.Lpr7_noepi:
	global_load_dwordx4 v[60:63], v[54:55], off
	global_load_dwordx4 v[64:67], v[48:49], off
	global_load_dwordx4 v[68:71], v[50:51], off
	global_load_dwordx4 v[72:75], v[54:55], off offset:64
	global_load_dwordx4 v[76:79], v[48:49], off offset:64
	global_load_dwordx4 v[80:83], v[50:51], off offset:64
	global_load_dwordx4 v[84:87], v[54:55], off offset:128
	global_load_dwordx4 v[88:91], v[48:49], off offset:128
	global_load_dwordx4 v[92:95], v[50:51], off offset:128
	global_load_dwordx4 v[96:99], v[54:55], off offset:192
	global_load_dwordx4 v[100:103], v[48:49], off offset:192
	global_load_dwordx4 v[104:107], v[50:51], off offset:192
	global_load_dwordx4 v[108:111], v[54:55], off offset:256
	global_load_dwordx4 v[112:115], v[48:49], off offset:256
	global_load_dwordx4 v[116:119], v[50:51], off offset:256
	global_load_dwordx4 v[120:123], v[54:55], off offset:320
	global_load_dwordx4 v[124:127], v[48:49], off offset:320
	global_load_dwordx4 v[128:131], v[50:51], off offset:320
	global_load_dwordx4 v[132:135], v[54:55], off offset:384
	global_load_dwordx4 v[136:139], v[48:49], off offset:384
	global_load_dwordx4 v[140:143], v[50:51], off offset:384
	global_load_dwordx4 v[144:147], v[54:55], off offset:448
	global_load_dwordx4 v[148:151], v[48:49], off offset:448
	global_load_dwordx4 v[152:155], v[50:51], off offset:448
	global_load_dwordx4 v[156:159], v[54:55], off offset:512
	global_load_dwordx4 v[160:163], v[48:49], off offset:512
	global_load_dwordx4 v[164:167], v[50:51], off offset:512
	global_load_dwordx4 v[168:171], v[54:55], off offset:576
	global_load_dwordx4 v[172:175], v[48:49], off offset:576
	global_load_dwordx4 v[176:179], v[50:51], off offset:576
	global_load_dwordx4 v[180:183], v[54:55], off offset:640
	global_load_dwordx4 v[184:187], v[48:49], off offset:640
	global_load_dwordx4 v[188:191], v[50:51], off offset:640
	s_lshl_b32 s3, s1, 11
	v_and_b32_e32 v5, 63, v5
	s_add_i32 s3, s3, 0
	v_lshl_add_u32 v2, v5, 4, s3
	s_cmp_gt_i32 s1, 1
	s_waitcnt vmcnt(30)
	v_mfma_f32_16x16x32_bf16 v[6:9], v[64:67], v[60:63], 0
	v_mfma_f32_16x16x32_bf16 v[10:13], v[68:71], v[60:63], 0
	s_waitcnt vmcnt(27)
	v_mfma_f32_16x16x32_bf16 v[6:9], v[76:79], v[72:75], v[6:9]
	v_mfma_f32_16x16x32_bf16 v[10:13], v[80:83], v[72:75], v[10:13]
	s_waitcnt vmcnt(24)
	v_mfma_f32_16x16x32_bf16 v[6:9], v[88:91], v[84:87], v[6:9]
	v_mfma_f32_16x16x32_bf16 v[10:13], v[92:95], v[84:87], v[10:13]
	s_waitcnt vmcnt(21)
	v_mfma_f32_16x16x32_bf16 v[6:9], v[100:103], v[96:99], v[6:9]
	v_mfma_f32_16x16x32_bf16 v[10:13], v[104:107], v[96:99], v[10:13]
	s_waitcnt vmcnt(18)
	v_mfma_f32_16x16x32_bf16 v[6:9], v[112:115], v[108:111], v[6:9]
	v_mfma_f32_16x16x32_bf16 v[10:13], v[116:119], v[108:111], v[10:13]
	s_waitcnt vmcnt(15)
	v_mfma_f32_16x16x32_bf16 v[6:9], v[124:127], v[120:123], v[6:9]
	v_mfma_f32_16x16x32_bf16 v[10:13], v[128:131], v[120:123], v[10:13]
	s_waitcnt vmcnt(12)
	v_mfma_f32_16x16x32_bf16 v[6:9], v[136:139], v[132:135], v[6:9]
	v_mfma_f32_16x16x32_bf16 v[10:13], v[140:143], v[132:135], v[10:13]
	s_waitcnt vmcnt(9)
	v_mfma_f32_16x16x32_bf16 v[6:9], v[148:151], v[144:147], v[6:9]
	v_mfma_f32_16x16x32_bf16 v[10:13], v[152:155], v[144:147], v[10:13]
	s_waitcnt vmcnt(6)
	v_mfma_f32_16x16x32_bf16 v[6:9], v[160:163], v[156:159], v[6:9]
	v_mfma_f32_16x16x32_bf16 v[10:13], v[164:167], v[156:159], v[10:13]
	s_waitcnt vmcnt(3)
	v_mfma_f32_16x16x32_bf16 v[6:9], v[172:175], v[168:171], v[6:9]
	v_mfma_f32_16x16x32_bf16 v[10:13], v[176:179], v[168:171], v[10:13]
	s_waitcnt vmcnt(0)
	v_mfma_f32_16x16x32_bf16 v[6:9], v[184:187], v[180:183], v[6:9]
	v_mfma_f32_16x16x32_bf16 v[10:13], v[188:191], v[180:183], v[10:13]
	s_nop 6
	ds_write_b128 v2, v[6:9]
	ds_write_b128 v2, v[10:13] offset:1024
	s_waitcnt lgkmcnt(0)
	s_barrier
	s_cbranch_scc1 .LBB0_1134
	s_lshl_b32 s1, s1, 4
	s_add_i32 s1, s1, s2
	v_lshl_or_b32 v6, v4, 2, s1
	v_lshlrev_b32_e32 v2, 10, v1
	v_ashrrev_i32_e32 v7, 31, v6
	v_mul_u32_u24_e32 v1, 0x1800, v1
	v_lshl_add_u64 v[10:11], v[6:7], 0, v[2:3]
	v_lshlrev_b32_e32 v2, 2, v1
	v_lshl_add_u64 v[8:9], s[70:71], 0, v[2:3]
	v_lshl_add_u64 v[6:7], v[6:7], 2, v[8:9]
	s_mov_b32 s1, 0x35000
	v_add_co_u32_e32 v6, vcc, s1, v6
	v_lshlrev_b64 v[46:47], 2, v[10:11]
	s_nop 0
	v_addc_co_u32_e32 v7, vcc, 0, v7, vcc
	v_mov_b32_e32 v6, v200
	v_mov_b32_e32 v7, v201
	v_mov_b32_e32 v8, v202
	v_mov_b32_e32 v9, v203
	v_lshl_add_u64 v[10:11], s[4:5], 0, v[46:47]
	v_mov_b32_e32 v10, v204
	v_mov_b32_e32 v11, v205
	v_mov_b32_e32 v12, v206
	v_mov_b32_e32 v13, v207
	s_and_b32 s1, s0, 0xfffffc0
	s_lshl_b32 s1, s1, 4
	s_add_i32 s1, s1, 0
	v_lshl_add_u32 v1, v5, 4, s1
	ds_read_b128 v[14:17], v1
	ds_read_b128 v[18:21], v1 offset:2048
	ds_read_b128 v[22:25], v1 offset:4096
	ds_read_b128 v[26:29], v1 offset:6144
	ds_read_b128 v[30:33], v1 offset:8192
	ds_read_b128 v[34:37], v1 offset:10240
	ds_read_b128 v[38:41], v1 offset:12288
	ds_read_b128 v[42:45], v1 offset:14336
	s_waitcnt lgkmcnt(6)
	v_pk_add_f32 v[4:5], v[16:17], v[20:21]
	v_pk_add_f32 v[14:15], v[14:15], v[18:19]
	s_waitcnt lgkmcnt(5)
	v_pk_add_f32 v[4:5], v[4:5], v[24:25]
	v_pk_add_f32 v[14:15], v[14:15], v[22:23]
	s_waitcnt lgkmcnt(4)
	v_pk_add_f32 v[4:5], v[4:5], v[28:29]
	v_pk_add_f32 v[14:15], v[14:15], v[26:27]
	s_waitcnt lgkmcnt(3)
	v_pk_add_f32 v[4:5], v[4:5], v[32:33]
	v_pk_add_f32 v[14:15], v[14:15], v[30:31]
	s_waitcnt lgkmcnt(2)
	v_pk_add_f32 v[4:5], v[4:5], v[36:37]
	v_pk_add_f32 v[14:15], v[14:15], v[34:35]
	s_waitcnt lgkmcnt(1)
	v_pk_add_f32 v[4:5], v[4:5], v[40:41]
	v_pk_add_f32 v[14:15], v[14:15], v[38:39]
	v_lshl_add_u64 v[46:47], s[68:69], 0, v[46:47]
	s_waitcnt lgkmcnt(0)
	v_pk_add_f32 v[4:5], v[4:5], v[44:45]
	v_pk_add_f32 v[14:15], v[14:15], v[42:43]
	s_mov_b32 s0, 0x3f9837f0
	v_add_co_u32_e32 v46, vcc, 0x14000000, v46
	s_waitcnt vmcnt(1)
	v_pk_add_f32 v[8:9], v[8:9], 1.0 op_sel_hi:[1,0]
	v_pk_add_f32 v[6:7], v[6:7], 1.0 op_sel_hi:[1,0]
	v_pk_mul_f32 v[4:5], v[4:5], v[8:9]
	v_pk_mul_f32 v[8:9], v[14:15], v[6:7]
	s_waitcnt vmcnt(0)
	v_pk_fma_f32 v[6:7], v[12:13], s[0:1], v[4:5] op_sel_hi:[1,0,1]
	v_pk_fma_f32 v[4:5], v[10:11], s[0:1], v[8:9] op_sel_hi:[1,0,1]
	v_addc_co_u32_e32 v47, vcc, 0, v47, vcc
	global_store_dwordx4 v[46:47], v[4:7], off sc1
	s_waitcnt vmcnt(0)
	s_mov_b64 s[6:7], exec
	s_mov_b64 exec, 1
	v_mov_b32_e32 v4, 1
	v_mov_b32_e32 v5, 0x27100
	global_atomic_add v5, v4, s[68:69]
	s_mov_b64 exec, s[6:7]

.LBB0_1197:
	s_cmp_lt_i32 s93, 9
	s_branch .LBB0_1251
	s_waitcnt vmcnt(0)
	s_barrier
	s_and_saveexec_b64 s[0:1], s[94:95]
	s_cbranch_execz .LBB0_1250
	s_add_i32 s2, 0, 0x24160
	v_mov_b32_e32 v0, s2
	s_waitcnt vmcnt(0) expcnt(0) lgkmcnt(0)
	ds_read_b32 v2, v0
	s_add_i32 s2, 0, 0x24164
	v_mov_b32_e32 v0, s2
	ds_read_b32 v0, v0
	s_waitcnt lgkmcnt(1)
	v_cmp_ne_u32_e32 vcc, 0, v2
	s_cbranch_vccnz .LBB0_1214
	v_readlane_b32 s2, v245, 0
	v_readlane_b32 s3, v245, 1
	s_load_dwordx2 s[6:7], s[2:3], 0x4
	s_add_u32 s2, s68, 0x4200
	s_addc_u32 s3, s69, 0
	s_add_u32 s4, s68, 0x4400
	s_addc_u32 s5, s69, 0
	s_waitcnt lgkmcnt(0)
	s_mul_i32 s15, s6, s33
	s_add_u32 s6, s68, 0x4500
	s_mul_i32 s15, s15, s7
	s_addc_u32 s7, s69, 0
	s_add_u32 s8, s68, 0x4600
	s_addc_u32 s9, s69, 0
	s_add_u32 s10, s68, 0x4700
	s_addc_u32 s11, s69, 0
	s_add_u32 s12, s68, 0x4800
	s_addc_u32 s13, s69, 0
	s_add_u32 s16, s68, 0x4900
	s_addc_u32 s17, s69, 0
	s_add_u32 s18, s68, 0x4a00
	s_addc_u32 s19, s69, 0
	s_add_u32 s20, s68, 0x4b00
	s_addc_u32 s21, s69, 0
	s_add_u32 s22, s68, 0x4c00
	s_addc_u32 s23, s69, 0
	s_add_u32 s24, s68, 0x4d00
	s_addc_u32 s25, s69, 0
	s_add_u32 s36, s68, 0x4e00
	s_addc_u32 s37, s69, 0
	s_add_u32 s38, s68, 0x4f00
	s_addc_u32 s39, s69, 0
	s_add_u32 s40, s68, 0x5000
	s_addc_u32 s41, s69, 0
	s_add_u32 s42, s68, 0x5100
	s_addc_u32 s43, s69, 0
	s_add_u32 s44, s68, 0x5200
	s_addc_u32 s45, s69, 0
	s_add_u32 s46, s68, 0x5300
	s_addc_u32 s47, s69, 0
	s_mov_b32 s26, 1
	v_mov_b32_e32 v16, 0
	s_branch .LBB0_1202

.LBB0_1251:
	s_cmp_lt_i32 s92, 9
	s_cselect_b64 s[0:1], -1, 0
	s_cmp_gt_i32 s93, 8
	s_cselect_b64 s[2:3], -1, 0
	s_cmpk_lt_i32 s14, 0x80
	s_cselect_b64 s[4:5], -1, 0
	s_and_b64 s[0:1], s[0:1], s[4:5]
	s_and_b64 s[0:1], s[0:1], s[2:3]
	s_andn2_b64 vcc, exec, s[0:1]
	s_cbranch_vccnz .LBB0_1254
	v_mov_b32_e32 v1, 0x27100
	s_mov_b32 s0, 0
.Lp8_spin:
	global_load_dword v2, v1, s[68:69] sc1
	s_waitcnt vmcnt(0)
	v_readfirstlane_b32 s1, v2
	s_cmpk_lt_u32 s1, 0x200
	s_cbranch_scc0 .Lp8_ok
	s_sleep 2
	s_add_i32 s0, s0, 1
	s_cmp_lt_u32 s0, 0x100000
	s_cbranch_scc1 .Lp8_spin
.Lp8_ok:
	buffer_inv sc1
	s_waitcnt vmcnt(0)
	v_mbcnt_hi_u32_b32 v0, -1, v215
	s_waitcnt vmcnt(0)
	v_and_b32_e32 v1, 64, v0
	v_add_u32_e32 v1, 64, v1
	v_xor_b32_e32 v2, 1, v0
	v_cmp_lt_i32_e32 vcc, v2, v1
	v_readlane_b32 s16, v245, 18
	v_readlane_b32 s20, v245, 22
	v_cndmask_b32_e32 v2, v0, v2, vcc
	v_lshlrev_b32_e32 v22, 2, v2
	v_xor_b32_e32 v2, 2, v0
	v_cmp_lt_i32_e32 vcc, v2, v1
	v_readlane_b32 s21, v245, 23
	v_readlane_b32 s22, v245, 24
	v_cndmask_b32_e32 v2, v0, v2, vcc
	v_lshlrev_b32_e32 v23, 2, v2
	v_xor_b32_e32 v2, 4, v0
	v_cmp_lt_i32_e32 vcc, v2, v1
	v_readlane_b32 s23, v245, 25
	v_readlane_b32 s28, v245, 30
	v_cndmask_b32_e32 v2, v0, v2, vcc
	v_lshlrev_b32_e32 v24, 2, v2
	v_xor_b32_e32 v2, 8, v0
	v_cmp_lt_i32_e32 vcc, v2, v1
	v_readlane_b32 s29, v245, 31
	v_readlane_b32 s30, v245, 32
	v_cndmask_b32_e32 v2, v0, v2, vcc
	v_readlane_b32 s31, v245, 33
	s_mov_b64 s[20:21], s[28:29]
	s_ashr_i32 s15, s14, 31
	v_lshlrev_b32_e32 v25, 2, v2
	v_xor_b32_e32 v2, 16, v0
	s_mov_b64 s[22:23], s[30:31]
	s_lshl_b64 s[0:1], s[14:15], 12
	v_cmp_lt_i32_e32 vcc, v2, v1
	s_add_u32 s2, s22, s0
	s_addc_u32 s3, s23, s1
	v_cndmask_b32_e32 v2, v0, v2, vcc
	s_add_i32 s0, s14, 0x4000
	v_lshlrev_b32_e32 v26, 2, v2
	v_xor_b32_e32 v2, 32, v0
	s_ashr_i32 s35, s34, 31
	s_ashr_i32 s1, s0, 31
	v_cmp_lt_i32_e32 vcc, v2, v1
	v_readlane_b32 s18, v245, 20
	v_readlane_b32 s19, v245, 21
	v_readlane_b32 s26, v245, 28
	v_readlane_b32 s27, v245, 29
	s_lshl_b64 s[4:5], s[34:35], 12
	s_lshl_b64 s[0:1], s[0:1], 12
	v_cndmask_b32_e32 v0, v0, v2, vcc
	v_lshlrev_b32_e32 v16, 4, v214
	v_mov_b32_e32 v17, 0
	s_mov_b64 s[18:19], s[26:27]
	s_add_u32 s6, s68, s0
	v_lshlrev_b32_e32 v27, 2, v0
	v_lshl_add_u64 v[18:19], s[18:19], 0, v[16:17]
	v_lshl_add_u64 v[20:21], s[20:21], 0, v[16:17]
	s_addc_u32 s7, s69, s1
	v_mov_b32_e32 v28, 0x3727c5ac
	s_mov_b32 s8, 0xf800000
	v_mov_b32_e32 v29, 0x260
	s_brev_b32 s9, 32
	v_readlane_b32 s17, v245, 19
	v_readlane_b32 s24, v245, 26
	v_readlane_b32 s25, v245, 27
